# HGRN c1: after staging an item, dummy-load the next item's IH/LF/LB tiles (L2 warm-up)
# baseline (speedup 1.0000x reference)
; DEV int hg_row0(int cidx, int b) { return (cidx < 4) ? (MM + b * 256 + cidx * 64) : (b * 8192 + (cidx - 4) * 64); }
; DEV void phase_hg_c1(const Params& p, char* smem) {
;     ...
;     const int r0 = hg_row0(cidx, b);
;     __syncthreads();
; #pragma unroll
;     for (int i = 0; i < 4; i++) {
;       int id = tid + i * 256; int s = id >> 4, cc = id & 15;
;       uint4 u = *(const uint4*)(IH + (size_t)(r0 + s) * 1024 + h * 128 + cc * 8);
;       uint4 lf = *(const uint4*)(LFp + (size_t)(r0 + s) * 1024 + h * 128 + cc * 8);
;       *(uint4*)(RB + s * 144 + cc * 8) = lf;
;       bf16_t* vt = Vt + (cc * 8) * 80 + s;
;       vt[0] = (bf16_t)(u.x & 0xffff); vt[80] = (bf16_t)(u.x >> 16); vt[160] = (bf16_t)(u.y & 0xffff); vt[240] = (bf16_t)(u.y >> 16);
;       vt[320] = (bf16_t)(u.z & 0xffff); vt[400] = (bf16_t)(u.z >> 16); vt[480] = (bf16_t)(u.w & 0xffff); vt[560] = (bf16_t)(u.w >> 16);
;     }
; #pragma unroll 1
;     for (int dir = 0; dir < 2; dir++) {
;       bf16_t* stg = dir ? RA : RB;
;       bf16_t* kot = dir ? RB : RA;
;       if (dir == 1) {
;         __syncthreads();
; #pragma unroll
;         for (int i = 0; i < 4; i++) {
;           int id = tid + i * 256; int s = id >> 4, cc = id & 15;
;           *(uint4*)(RA + s * 144 + cc * 8) = *(const uint4*)(LBp + (size_t)(r0 + s) * 1024 + h * 128 + cc * 8);
;         }
.LBB0_305:
	s_ashr_i32 s11, s10, 4
	s_and_b32 s0, s10, 15
	s_bfe_u32 s1, s10, 0x10003
	s_lshl_b32 s2, s11, 6
	s_cmp_lt_i32 s11, 4
	s_movk_i32 s6, 0xff00
	s_cselect_b32 s3, 8, 13
	s_cselect_b32 s6, 0x4000, s6
	s_lshl_b32 s1, s1, s3
	s_add_i32 s2, s6, s2
	s_add_i32 s1, s2, s1
	s_lshl_b32 s2, s10, 8
	v_add_u32_e32 v22, s1, v36
	s_and_b32 s52, s2, 0x700
	v_ashrrev_i32_e32 v23, 31, v22
	v_lshl_add_u64 v[58:59], v[4:5], 0, s[52:53]
	v_lshl_add_u64 v[60:61], v[6:7], 0, s[52:53]
	v_bfe_u32 v160, v195, 2, 4
	v_lshrrev_b32_e32 v161, 6, v195
	v_and_b32_e32 v166, 3, v195
	v_lshl_or_b32 v161, v161, 2, v166
	v_lshrrev_b32_e32 v166, 4, v195
	v_sub_u32_e32 v160, v160, v166
	v_and_b32_e32 v166, 15, v195
	v_sub_u32_e32 v161, v161, v166
	v_lshlrev_b32_e32 v162, 11, v160
	v_lshl_add_u32 v162, v161, 4, v162
	v_ashrrev_i32_e32 v163, 31, v162
	v_mul_i32_i24_e32 v164, 0x500, v161
	v_lshl_add_u32 v164, v160, 1, v164
	v_lshlrev_b64 v[22:23], 11, v[22:23]
	v_add_u32_e32 v24, s1, v39
	v_ashrrev_i32_e32 v25, 31, v24
	v_lshlrev_b64 v[24:25], 11, v[24:25]
	v_add_u32_e32 v26, s1, v42
	v_ashrrev_i32_e32 v27, 31, v26
	v_lshlrev_b64 v[26:27], 11, v[26:27]
	v_add_u32_e32 v28, s1, v45
	v_ashrrev_i32_e32 v29, 31, v28
	v_lshlrev_b64 v[62:63], 11, v[28:29]
	s_waitcnt lgkmcnt(0)
	s_barrier
	v_lshl_add_u64 v[28:29], v[58:59], 0, v[22:23]
	v_lshl_add_u64 v[28:29], v[28:29], 0, v[162:163]
	global_load_dwordx4 v[168:171], v[28:29], off
	v_lshl_add_u64 v[30:31], v[60:61], 0, v[22:23]
	global_load_dwordx4 v[172:175], v[30:31], off
	v_lshl_add_u64 v[28:29], v[58:59], 0, v[24:25]
	v_lshl_add_u64 v[28:29], v[28:29], 0, v[162:163]
	global_load_dwordx4 v[176:179], v[28:29], off
	v_lshl_add_u64 v[30:31], v[60:61], 0, v[24:25]
	global_load_dwordx4 v[180:183], v[30:31], off
	v_lshl_add_u64 v[28:29], v[58:59], 0, v[26:27]
	v_lshl_add_u64 v[28:29], v[28:29], 0, v[162:163]
	global_load_dwordx4 v[184:187], v[28:29], off
	v_lshl_add_u64 v[30:31], v[60:61], 0, v[26:27]
	global_load_dwordx4 v[188:191], v[30:31], off
	v_lshl_add_u64 v[28:29], v[58:59], 0, v[62:63]
	v_lshl_add_u64 v[28:29], v[28:29], 0, v[162:163]
	global_load_dwordx4 v[236:239], v[28:29], off
	v_lshl_add_u64 v[30:31], v[60:61], 0, v[62:63]
	global_load_dwordx4 v[240:243], v[30:31], off
	s_lshl_b32 s12, s0, 1
	s_cmp_gt_i32 s11, 3
	s_cselect_b32 s0, 0x87, 3
	s_sub_i32 s13, s0, s11
	s_mov_b32 s14, 0
	s_mov_b64 s[6:7], -1
	s_mov_b64 s[0:1], 0
	s_waitcnt vmcnt(6)
	v_add_u32_e32 v17, v2, v37
	ds_write_b128 v17, v[172:175] offset:20480
	v_add_u32_e32 v165, v38, v164
	ds_write_b16 v165, v168 offset:40960
	ds_write_b16_d16_hi v165, v168 offset:41120
	ds_write_b16 v165, v169 offset:41280
	ds_write_b16_d16_hi v165, v169 offset:41440
	ds_write_b16 v165, v170 offset:41600
	ds_write_b16_d16_hi v165, v170 offset:41760
	ds_write_b16 v165, v171 offset:41920
	ds_write_b16_d16_hi v165, v171 offset:42080
	s_waitcnt vmcnt(4)
	v_add_u32_e32 v17, v2, v40
	ds_write_b128 v17, v[180:183] offset:20480
	v_add_u32_e32 v165, v41, v164
	ds_write_b16 v165, v176 offset:40960
	ds_write_b16_d16_hi v165, v176 offset:41120
	ds_write_b16 v165, v177 offset:41280
	ds_write_b16_d16_hi v165, v177 offset:41440
	ds_write_b16 v165, v178 offset:41600
	ds_write_b16_d16_hi v165, v178 offset:41760
	ds_write_b16 v165, v179 offset:41920
	ds_write_b16_d16_hi v165, v179 offset:42080
	s_waitcnt vmcnt(2)
	v_add_u32_e32 v17, v2, v43
	ds_write_b128 v17, v[188:191] offset:20480
	v_add_u32_e32 v165, v44, v164
	ds_write_b16 v165, v184 offset:40960
	ds_write_b16_d16_hi v165, v184 offset:41120
	ds_write_b16 v165, v185 offset:41280
	ds_write_b16_d16_hi v165, v185 offset:41440
	ds_write_b16 v165, v186 offset:41600
	ds_write_b16_d16_hi v165, v186 offset:41760
	ds_write_b16 v165, v187 offset:41920
	ds_write_b16_d16_hi v165, v187 offset:42080
	s_waitcnt vmcnt(0)
	v_add_u32_e32 v17, v2, v46
	ds_write_b128 v17, v[240:243] offset:20480
	v_add_u32_e32 v165, v47, v164
	ds_write_b16 v165, v236 offset:40960
	ds_write_b16_d16_hi v165, v236 offset:41120
	ds_write_b16 v165, v237 offset:41280
	ds_write_b16_d16_hi v165, v237 offset:41440
	ds_write_b16 v165, v238 offset:41600
	ds_write_b16_d16_hi v165, v238 offset:41760
	ds_write_b16 v165, v239 offset:41920
	ds_write_b16_d16_hi v165, v239 offset:42080
	v_lshl_add_u64 v[54:55], v[12:13], 0, s[52:53]
	v_lshl_add_u64 v[28:29], v[54:55], 0, v[22:23]
	global_load_dwordx4 v[168:171], v[28:29], off
	v_lshl_add_u64 v[28:29], v[54:55], 0, v[24:25]
	global_load_dwordx4 v[172:175], v[28:29], off
	v_lshl_add_u64 v[28:29], v[54:55], 0, v[26:27]
	global_load_dwordx4 v[176:179], v[28:29], off
	v_lshl_add_u64 v[28:29], v[54:55], 0, v[62:63]
	global_load_dwordx4 v[180:183], v[28:29], off
	s_mov_b32 s98, 0x400000
	s_mov_b32 s99, 0
	v_lshl_add_u64 v[28:29], v[58:59], 0, v[22:23]
	v_lshl_add_u64 v[28:29], v[28:29], 0, v[162:163]
	v_lshl_add_u64 v[28:29], v[28:29], 0, s[98:99]
	global_load_dwordx4 v[184:187], v[28:29], off
	v_lshl_add_u64 v[30:31], v[60:61], 0, v[22:23]
	v_lshl_add_u64 v[30:31], v[30:31], 0, s[98:99]
	global_load_dwordx4 v[184:187], v[30:31], off
	v_lshl_add_u64 v[28:29], v[54:55], 0, v[22:23]
	v_lshl_add_u64 v[28:29], v[28:29], 0, s[98:99]
	global_load_dwordx4 v[184:187], v[28:29], off
	v_lshl_add_u64 v[28:29], v[58:59], 0, v[24:25]
	v_lshl_add_u64 v[28:29], v[28:29], 0, v[162:163]
	v_lshl_add_u64 v[28:29], v[28:29], 0, s[98:99]
	global_load_dwordx4 v[184:187], v[28:29], off
	v_lshl_add_u64 v[30:31], v[60:61], 0, v[24:25]
	v_lshl_add_u64 v[30:31], v[30:31], 0, s[98:99]
	global_load_dwordx4 v[184:187], v[30:31], off
	v_lshl_add_u64 v[28:29], v[54:55], 0, v[24:25]
	v_lshl_add_u64 v[28:29], v[28:29], 0, s[98:99]
	global_load_dwordx4 v[184:187], v[28:29], off
	v_lshl_add_u64 v[28:29], v[58:59], 0, v[26:27]
	v_lshl_add_u64 v[28:29], v[28:29], 0, v[162:163]
	v_lshl_add_u64 v[28:29], v[28:29], 0, s[98:99]
	global_load_dwordx4 v[184:187], v[28:29], off
	v_lshl_add_u64 v[30:31], v[60:61], 0, v[26:27]
	v_lshl_add_u64 v[30:31], v[30:31], 0, s[98:99]
	global_load_dwordx4 v[184:187], v[30:31], off
	v_lshl_add_u64 v[28:29], v[54:55], 0, v[26:27]
	v_lshl_add_u64 v[28:29], v[28:29], 0, s[98:99]
	global_load_dwordx4 v[184:187], v[28:29], off
	v_lshl_add_u64 v[28:29], v[58:59], 0, v[62:63]
	v_lshl_add_u64 v[28:29], v[28:29], 0, v[162:163]
	v_lshl_add_u64 v[28:29], v[28:29], 0, s[98:99]
	global_load_dwordx4 v[184:187], v[28:29], off
	v_lshl_add_u64 v[30:31], v[60:61], 0, v[62:63]
	v_lshl_add_u64 v[30:31], v[30:31], 0, s[98:99]
	global_load_dwordx4 v[184:187], v[30:31], off
	v_lshl_add_u64 v[28:29], v[54:55], 0, v[62:63]
	v_lshl_add_u64 v[28:29], v[28:29], 0, s[98:99]
	global_load_dwordx4 v[184:187], v[28:29], off
	s_branch .LBB0_307
